# v25: v18 plus one static s_setprio 1 for waves 4-7 at the start of the two attention phases (younger half of each SIMD pair)
# speedup vs baseline: 1.0057x; 1.0056x over previous
; __device__ __forceinline__ int fresh_lane() { unsigned o_ = ~0u; asm volatile("" : "+s"(o_)); return (int)__builtin_amdgcn_mbcnt_hi(o_, __builtin_amdgcn_mbcnt_lo(o_, 0u)); }
; __global__ void __launch_bounds__(NWAVES * 64, 2) mega_fwd(Args args) {
;     ...
;         } else if (code == 14) {
; #pragma unroll 1
;             for (int u_ = vcu; u_ < 512 * PROBE_REP_C; u_ += G) { const int u = u_ & 511;
;                 int bh, qb; wg_unit_map(u, bh, qb);
;                 const int ln_ = pg8::fresh_lane(), r32 = ln_ & 31, hi = ln_ >> 5, tid = wave * 64 + ln_;
;                 const int b = bh >> 3, h = bh & 7, tokb = b * SEQ, q0 = qb * 256, qw = q0 + 32 * wave;
;                 bf16x8 qf[12]; load_qf<12>(qf, QC + (size_t)(tokb + qw + r32) * 1536 + h * 192, hi);
;                 { const int pos = qw + r32;
;                   rope_frag_pair(qf[8], qf[10], cos64 + pos * 32 + 8 * hi, sin64 + pos * 32 + 8 * hi); rope_frag_pair(qf[9], qf[11], cos64 + pos * 32 + 16 + 8 * hi, sin64 + pos * 32 + 16 + 8 * hi); }
;                 f32x16 o[4]; float m_, l_; zero_state(o, m_, l_);
;                 CtlCausal ctl{qw, r32, hi, false, 0, 0u};
;                 wg_attention<8, 4, CtlCausal>(lds, KV + h * 128, KV_LD, Z + 768, CD_INP, (const bf16*)(ap->ws + WS_VTC) + (size_t)(h * 128) * VTP, tokb, 0, (q0 + 256) >> 6, qf, 0.07216878364870322f * 1.4426950408889634f, ctl, o, m_, l_, tid, r32, hi);
.LBB0_84:
	s_load_dwordx2 s[72:73], s[0:1], 0xa8
	v_writelane_b32 v255, s12, 14
	s_waitcnt lgkmcnt(0)
	v_mbcnt_lo_u32_b32 v0, s3, 0
	v_mbcnt_hi_u32_b32 v244, s3, v0
	v_writelane_b32 v255, s13, 15
	v_writelane_b32 v255, s11, 16
	v_writelane_b32 v255, s28, 17
	s_waitcnt lgkmcnt(0)
	s_add_u32 s3, s72, 0x53200000
	v_writelane_b32 v255, s3, 18
	s_addc_u32 s3, s73, 0
	v_writelane_b32 v255, s3, 19
	s_mov_b64 s[8:9], 0
	v_writelane_b32 v255, s8, 20
	s_lshl_b32 s3, s2, 3
	s_lshl_b32 s77, s93, 6
	v_writelane_b32 v255, s9, 21
	s_add_i32 s76, s3, s93
	s_lshl_b32 s78, s48, 3
	v_writelane_b32 v255, s93, 22
	s_mov_b64 s[6:7], -1
	s_cmp_lt_i32 s18, 7
	s_mov_b64 s[62:63], 0
	s_mov_b64 s[60:61], 0
	s_mov_b64 s[90:91], 0
	v_writelane_b32 v255, s18, 23
	s_cbranch_scc1 .LBB0_256
	s_cmp_gt_i32 s18, 10
	s_cbranch_scc0 .LBB0_168
	s_cmp_gt_i32 s18, 11
	s_cbranch_scc0 .LBB0_158
	s_cmp_gt_i32 s18, 13
	s_cbranch_scc0 .LBB0_155
	s_cmp_eq_u32 s18, 14
	s_mov_b64 s[62:63], -1
	s_cbranch_scc0 .LBB0_154
	s_cmpk_gt_i32 s55, 0x1ff
	s_cbranch_scc1 .LBB0_153
	v_readlane_b32 s101, v255, 22
	s_cmp_lt_u32 s101, 4
	s_cbranch_scc1 .Lprio_skip_2
	s_setprio 1
.Lprio_skip_2:
	v_readlane_b32 s3, v255, 22
	s_lshl_b32 s84, s3, 5
	s_add_u32 s6, s72, 0x3d200000
	s_addc_u32 s7, s73, 0
	s_add_u32 s86, s72, 0x100000
	s_addc_u32 s87, s73, 0
	s_add_u32 s92, s72, 0x180000
	s_addc_u32 s93, s73, 0
	s_add_u32 s3, s72, 0x40200000
	s_addc_u32 s46, s73, 0
	s_add_u32 s47, s72, 0x26200600
	s_addc_u32 s50, s73, 0
	s_add_u32 s64, s72, 0x4ae00000
	s_addc_u32 s65, s73, 0
	s_add_u32 s94, s72, 0x35200000
	s_addc_u32 s95, s73, 0
	v_mov_b64_e32 v[182:183], s[6:7]
	s_mov_b32 s66, s55
	s_branch .LBB0_92

; __global__ void __launch_bounds__(NWAVES * 64, 2) mega_fwd(Args args) {
;     ...
;         } else if (code == 6) {
;             const float lamA = wave_sum(ap->in[7][lane] * ap->in[7][64 + lane], lane), lamB = wave_sum(ap->in[7][128 + lane] * ap->in[7][192 + lane], lane);
;             const float lam = __expf(lamA) - __expf(lamB) + 0.2f;
;             const int r32 = lane & 31, hi = lane >> 5;
;             bf16* STASH = (bf16*)(ap->ws + WS_T);
; #pragma unroll 1
;             for (int u_ = vcu; u_ < 512 * PROBE_REP_A; u_ += G) { const int u = u_ & 511;
;                 int bh, qb; wg_unit_map(u, bh, qb);
;                 const int b = bh >> 3, h = bh & 7, tokb = b * SEQ, q0 = qb * 256, qw = q0 + 32 * wave;
;                 const bf16* vt = (const bf16*)(ap->ws + WS_VTA) + (size_t)(h * 128) * VTP;
;                 f32x16 o[4]; float m_, l_;
; #pragma unroll 1
;                 for (int mp = 0; mp < 2; ++mp) {
;                     bf16x8 qf[4]; load_qf<4>(qf, Z + (size_t)(tokb + qw + r32) * AB_IN + h * 128 + mp * 64, hi);
;                     zero_state(o, m_, l_);
;                     CtlCausal ctl{qw, r32, hi, false, 0, 0u};
;                     wg_attention128<4>(lds, Z + 1024 + h * 128 + mp * 64, AB_IN, vt, tokb, (q0 + 256) >> 7, qf, 0.125f * 1.4426950408889634f, ctl, o, m_, l_, tid, r32, hi);
.LBB0_256:
	s_and_b64 vcc, exec, s[6:7]
	s_cbranch_vccz .LBB0_330
	s_mov_b64 s[6:7], -1
	v_writelane_b32 v255, s6, 20
	s_cmp_gt_i32 s18, 3
	s_nop 0
	v_writelane_b32 v255, s7, 21
	s_cbranch_scc0 .LBB0_330
	s_cmp_gt_i32 s18, 4
	s_mov_b64 s[90:91], -1
	s_cbranch_scc0 .LBB0_329
	s_cmp_gt_i32 s18, 5
	s_mov_b64 s[6:7], -1
	s_cbranch_scc0 .LBB0_315
	v_readlane_b32 s101, v255, 22
	s_cmp_lt_u32 s101, 4
	s_cbranch_scc1 .Lprio_skip_1
	s_setprio 1
.Lprio_skip_1:
	s_load_dwordx2 s[6:7], s[0:1], 0x38
	v_lshlrev_b32_e32 v3, 2, v244
	v_xor_b32_e32 v5, 4, v3
	v_xor_b32_e32 v6, 8, v3
	v_xor_b32_e32 v7, 32, v3
	s_waitcnt lgkmcnt(0)
	global_load_dword v0, v3, s[6:7]
	global_load_dword v2, v3, s[6:7] offset:256
	v_xor_b32_e32 v8, 64, v3
	v_xor_b32_e32 v9, 0x80, v3
	v_writelane_b32 v255, s62, 31
	v_add_u32_e32 v173, s77, v244
	v_add_u32_e32 v177, 0x200, v173
	v_writelane_b32 v255, s63, 32
	v_writelane_b32 v255, s60, 14
	v_mov_b32_e32 v208, 0x2000
	v_and_b32_e32 v213, 31, v244
	v_writelane_b32 v255, s61, 15
	s_cmpk_gt_i32 s55, 0x1ff
	v_ashrrev_i32_e32 v209, 31, v177
	s_waitcnt vmcnt(0)
	v_mul_f32_e32 v4, v0, v2
	ds_bpermute_b32 v4, v5, v4
	s_waitcnt lgkmcnt(0)
	v_fmac_f32_e32 v4, v0, v2
	ds_bpermute_b32 v0, v6, v4
	s_waitcnt lgkmcnt(0)
	v_add_f32_e32 v0, v4, v0
	v_xor_b32_e32 v4, 16, v3
	global_load_dword v10, v3, s[6:7] offset:512
	s_nop 0
	global_load_dword v3, v3, s[6:7] offset:768
	ds_bpermute_b32 v2, v4, v0
	s_waitcnt lgkmcnt(0)
	v_add_f32_e32 v0, v0, v2
	ds_bpermute_b32 v2, v7, v0
	s_waitcnt lgkmcnt(0)
	v_add_f32_e32 v0, v0, v2
	ds_bpermute_b32 v2, v8, v0
	s_waitcnt lgkmcnt(0)
	v_add_f32_e32 v0, v0, v2
	ds_bpermute_b32 v2, v9, v0
	s_waitcnt vmcnt(0)
	v_mul_f32_e32 v11, v10, v3
	ds_bpermute_b32 v5, v5, v11
	s_waitcnt lgkmcnt(0)
	v_fmac_f32_e32 v5, v10, v3
	ds_bpermute_b32 v3, v6, v5
	v_lshrrev_b32_e32 v6, 5, v244
	v_lshlrev_b32_e32 v212, 3, v6
	v_lshlrev_b32_e32 v215, 4, v6
	v_lshlrev_b32_e32 v172, 2, v6
	s_waitcnt lgkmcnt(0)
	v_add_f32_e32 v3, v5, v3
	ds_bpermute_b32 v4, v4, v3
	v_ashrrev_i32_e32 v5, 31, v173
	v_lshrrev_b32_e32 v185, 28, v5
	s_waitcnt lgkmcnt(0)
	v_add_f32_e32 v3, v3, v4
	ds_bpermute_b32 v4, v7, v3
	s_waitcnt lgkmcnt(0)
	v_add_f32_e32 v3, v3, v4
	ds_bpermute_b32 v4, v8, v3
	s_waitcnt lgkmcnt(0)
	v_add_f32_e32 v3, v3, v4
	ds_bpermute_b32 v4, v9, v3
	s_cbranch_scc1 .LBB0_289
	v_add_f32_e32 v0, v0, v2
	s_waitcnt lgkmcnt(0)
	v_add_f32_e32 v2, v3, v4
	v_mul_f32_e32 v0, 0x3fb8aa3b, v0
	v_mul_f32_e32 v2, 0x3fb8aa3b, v2
	v_exp_f32_e32 v0, v0
	v_exp_f32_e32 v2, v2
	s_add_u32 s44, s72, 0x39200000
	v_readlane_b32 s3, v255, 22
	s_addc_u32 s45, s73, 0
	v_sub_f32_e32 v0, v0, v2
	v_add_f32_e32 v174, 0x3e4ccccd, v0
	v_lshrrev_b32_e32 v0, 29, v5
	v_add_u32_e32 v0, v173, v0
	v_ashrrev_i32_e32 v2, 3, v0
	v_and_b32_e32 v0, 0xffffff8, v0
	v_sub_u32_e32 v0, v173, v0
	v_lshlrev_b32_e32 v176, 4, v0
	v_lshrrev_b32_e32 v0, 29, v209
	v_add_u32_e32 v0, v177, v0
	v_ashrrev_i32_e32 v3, 3, v0
	v_and_b32_e32 v0, 0xffffff8, v0
	v_sub_u32_e32 v0, v177, v0
	v_lshlrev_b32_e32 v180, 4, v0
	v_add_u32_e32 v0, v173, v185
	v_ashrrev_i32_e32 v4, 4, v0
	v_and_b32_e32 v0, 0xffffff0, v0
	v_sub_u32_e32 v0, v173, v0
	v_lshlrev_b32_e32 v184, 4, v0
	v_lshrrev_b32_e32 v0, 28, v209
	v_add_u32_e32 v0, v177, v0
	v_ashrrev_i32_e32 v5, 4, v0
	v_and_b32_e32 v0, 0xffffff0, v0
	v_sub_u32_e32 v0, v177, v0
	v_lshlrev_b32_e32 v188, 4, v0
	v_add_u32_e32 v0, 0x400, v173
	v_ashrrev_i32_e32 v6, 31, v0
	v_lshrrev_b32_e32 v6, 28, v6
	v_add_u32_e32 v6, v0, v6
	v_ashrrev_i32_e32 v7, 4, v6
	v_and_b32_e32 v6, 0xffffff0, v6
	v_sub_u32_e32 v0, v0, v6
	s_lshl_b32 s50, s3, 5
	v_lshlrev_b32_e32 v192, 4, v0
	v_add_u32_e32 v0, 0x600, v173
	s_add_u32 s64, s72, 0x45a00000
	v_ashrrev_i32_e32 v6, 31, v0
	s_addc_u32 s65, s73, 0
	v_lshrrev_b32_e32 v6, 28, v6
	s_add_u32 s84, s72, 0x26200000
	v_add_u32_e32 v6, v0, v6
	s_addc_u32 s85, s73, 0
	v_ashrrev_i32_e32 v8, 4, v6
	v_and_b32_e32 v6, 0xffffff0, v6
	s_movk_i32 s3, 0x90
	s_add_u32 s68, s72, 0x26200800
	v_mad_u64_u32 v[190:191], s[6:7], v5, s4, v[188:189]
	v_mad_u64_u32 v[194:195], s[6:7], v7, s4, v[192:193]
	v_sub_u32_e32 v0, v0, v6
	v_mul_lo_u32 v189, v2, s3
	v_mul_lo_u32 v193, v3, s3
	s_movk_i32 s3, 0x108
	s_addc_u32 s77, s73, 0
	v_lshlrev_b32_e32 v214, 4, v0
	v_mul_lo_u32 v245, v4, s3
	v_mul_lo_u32 v246, v5, s3
	v_mul_lo_u32 v247, v7, s3
	v_mul_lo_u32 v248, v8, s3
	v_or_b32_e32 v20, 2, v172
	v_mad_u64_u32 v[178:179], s[6:7], v2, s75, v[176:177]
	v_mad_u64_u32 v[182:183], s[6:7], v3, s75, v[180:181]
	v_mad_u64_u32 v[186:187], s[6:7], v4, s4, v[184:185]
	v_mad_u64_u32 v[216:217], s[6:7], v8, s4, v[214:215]
	v_add_u32_e32 v0, 0, v189
	v_add_u32_e32 v2, 0, v193
	v_add_u32_e32 v3, 0, v245
	v_add_u32_e32 v4, 0, v246
	v_add_u32_e32 v5, 0, v247
	v_add_u32_e32 v6, 0, v248
	v_mul_u32_u24_e32 v7, 0x108, v213
	v_add_u32_e32 v8, -8, v213
	v_add_u32_e32 v9, -9, v213
	v_add_u32_e32 v10, -10, v213
	v_add_u32_e32 v11, -11, v213
	v_add_u32_e32 v12, -16, v213
	v_subrev_u32_e32 v13, 17, v213
	v_subrev_u32_e32 v14, 18, v213
	v_subrev_u32_e32 v15, 19, v213
	v_subrev_u32_e32 v16, 24, v213
	v_subrev_u32_e32 v17, 25, v213
	v_subrev_u32_e32 v18, 26, v213
	v_subrev_u32_e32 v19, 27, v213
	v_cmp_gt_i32_e64 s[10:11], v20, v213
	v_or_b32_e32 v20, 3, v172
	s_add_u32 s88, s72, 0x35200000
	v_readlane_b32 s3, v255, 7
	v_mov_b32_e32 v179, v1
	v_mov_b32_e32 v183, v1
	v_mov_b32_e32 v187, v1
	v_mov_b32_e32 v191, v1
	v_mov_b32_e32 v195, v1
	v_mov_b32_e32 v217, v1
	v_cmp_gt_i32_e64 s[6:7], v172, v213
	v_cmp_lt_i32_e64 s[8:9], v172, v213
	v_cmp_gt_i32_e64 s[12:13], v20, v213
	v_cmp_gt_i32_e64 s[14:15], v172, v8
	v_cmp_gt_i32_e64 s[16:17], v172, v9
	v_cmp_gt_i32_e64 s[18:19], v172, v10
	v_cmp_gt_i32_e64 s[20:21], v172, v11
	v_cmp_gt_i32_e64 s[22:23], v172, v12
	v_cmp_gt_i32_e64 s[24:25], v172, v13
	v_cmp_gt_i32_e64 s[26:27], v172, v14
	v_cmp_gt_i32_e64 s[28:29], v172, v15
	v_cmp_gt_i32_e64 s[30:31], v172, v16
	v_cmp_gt_i32_e64 s[34:35], v172, v17
	v_cmp_gt_i32_e64 s[36:37], v172, v18
	v_cmp_gt_i32_e64 s[38:39], v172, v19
	s_addc_u32 s89, s73, 0
	v_mov_b32_e32 v175, v174
	v_add3_u32 v249, v7, v212, s3
	v_lshlrev_b32_e32 v218, 1, v212
	v_lshlrev_b32_e32 v220, 1, v172
	v_add_u32_e32 v250, v0, v176
	v_add_u32_e32 v251, v2, v180
	v_add3_u32 v252, v3, v184, s69
	v_add3_u32 v253, v4, v188, s69
	v_add3_u32 v254, v5, v192, s69
	v_add3_u32 v238, v6, v214, s69
	s_mov_b32 s79, s55
	s_branch .LBB0_263
